# adds: memory-attention epilogue gate loads issued in the unit prologue; band softmax far-tile path trimmed
# speedup vs baseline: 1.0083x; 1.0083x over previous
.LBB0_402:
	v_sub_f32_e32 v17, v17, v15
	v_sub_f32_e32 v16, v16, v15
	v_exp_f32_e32 v68, v17
	v_exp_f32_e32 v17, v16
	v_sub_f32_e32 v16, v27, v15
	v_exp_f32_e32 v153, v16
	v_sub_f32_e32 v16, v26, v15
	v_exp_f32_e32 v151, v16
	v_sub_f32_e32 v16, v25, v15
	v_exp_f32_e32 v149, v16
	v_sub_f32_e32 v16, v24, v15
	v_exp_f32_e32 v147, v16
	v_sub_f32_e32 v16, v23, v15
	v_exp_f32_e32 v145, v16
	v_sub_f32_e32 v16, v22, v15
	v_sub_f32_e32 v7, v7, v15
	v_exp_f32_e32 v143, v16
	v_exp_f32_e32 v155, v7
	v_sub_f32_e32 v7, v19, v15
	v_exp_f32_e32 v135, v7
	v_sub_f32_e32 v7, v18, v15
	v_exp_f32_e32 v133, v7
	v_sub_f32_e32 v7, v9, v15
	v_sub_f32_e32 v16, v21, v15
	v_exp_f32_e32 v131, v7
	v_sub_f32_e32 v7, v8, v15
	v_exp_f32_e32 v141, v16
	v_sub_f32_e32 v16, v20, v15
	v_exp_f32_e32 v129, v7
	v_cvt_pk_bf16_f32 v34, v143, v145
	v_cvt_pk_bf16_f32 v35, v147, v149
	v_cvt_pk_bf16_f32 v36, v151, v153
	v_cvt_pk_bf16_f32 v37, v17, v68
	v_mov_b32_e32 v7, v1
	v_exp_f32_e32 v139, v16
	v_sub_f32_e32 v6, v6, v15
	v_add_u32_e32 v16, v93, v7
	v_add_u32_e32 v69, 0xd000, v16
	ds_read2_b64 v[18:21], v69 offset1:4
	v_exp_f32_e32 v137, v6
	ds_read2_b64 v[6:9], v69 offset0:8 offset1:12
	v_cvt_pk_bf16_f32 v62, v129, v131
	v_cvt_pk_bf16_f32 v63, v133, v135
	v_cvt_pk_bf16_f32 v64, v137, v155
	v_cvt_pk_bf16_f32 v65, v139, v141
	v_add_u32_e32 v15, 0xd800, v16
	v_add_f32_e32 v0, 0, v0
	s_waitcnt lgkmcnt(1)
	v_mfma_f32_16x16x32_bf16 v[2:5], v[18:21], v[62:65], v[2:5]
	ds_read2_b64 v[18:21], v15 offset0:32 offset1:36
	v_add_f32_e32 v0, v156, v0
	s_add_u32 s18, s40, s47
	s_waitcnt lgkmcnt(1)
	v_mfma_f32_16x16x32_bf16 v[30:33], v[6:9], v[34:37], v[2:5]
	v_mad_i64_i32 v[66:67], s[14:15], v90, s59, 0
	s_addc_u32 s19, s41, 0
	s_nop 0
	ds_read2_b64 v[2:5], v15 offset0:40 offset1:44
	v_add_u32_e32 v15, 0xe000, v16
	s_waitcnt lgkmcnt(1)
	v_mfma_f32_16x16x32_bf16 v[6:9], v[18:21], v[62:65], v[58:61]
	ds_read2_b64 v[18:21], v15 offset0:64 offset1:68
	v_mov_b32_e32 v93, v1
	v_readlane_b32 s6, v236, 9
	s_waitcnt lgkmcnt(1)
	v_mfma_f32_16x16x32_bf16 v[26:29], v[2:5], v[34:37], v[6:9]
	ds_read2_b64 v[2:5], v15 offset0:72 offset1:76
	v_add_u32_e32 v15, 0xe800, v16
	v_readlane_b32 s7, v236, 10
	s_waitcnt lgkmcnt(1)
	v_mfma_f32_16x16x32_bf16 v[6:9], v[18:21], v[62:65], v[54:57]
	ds_read2_b64 v[18:21], v15 offset0:96 offset1:100
	s_waitcnt lgkmcnt(1)
	v_mfma_f32_16x16x32_bf16 v[22:25], v[2:5], v[34:37], v[6:9]
	ds_read2_b64 v[2:5], v15 offset0:104 offset1:108
	v_add_u32_e32 v15, 0xf000, v16
	s_waitcnt lgkmcnt(1)
	v_mfma_f32_16x16x32_bf16 v[6:9], v[18:21], v[62:65], v[50:53]
	s_nop 2
	ds_read2_b64 v[50:53], v15 offset0:128 offset1:132
	s_waitcnt lgkmcnt(1)
	v_mfma_f32_16x16x32_bf16 v[18:21], v[2:5], v[34:37], v[6:9]
	ds_read2_b64 v[2:5], v15 offset0:136 offset1:140
	v_add_u32_e32 v15, 0xf800, v16
	s_waitcnt lgkmcnt(1)
	v_mfma_f32_16x16x32_bf16 v[6:9], v[50:53], v[62:65], v[46:49]
	s_nop 2
	ds_read2_b64 v[46:49], v15 offset0:160 offset1:164
	ds_read2_b64 v[50:53], v15 offset0:168 offset1:172
	v_add_u32_e32 v15, 0x3000, v69
	s_waitcnt lgkmcnt(2)
	v_mfma_f32_16x16x32_bf16 v[6:9], v[2:5], v[34:37], v[6:9]
	s_waitcnt lgkmcnt(1)
	v_mfma_f32_16x16x32_bf16 v[2:5], v[46:49], v[62:65], v[42:45]
	ds_read2_b64 v[46:49], v15 offset0:192 offset1:196
	ds_read2_b64 v[54:57], v15 offset0:200 offset1:204
	v_add_u32_e32 v15, 0x3800, v69
	v_lshl_add_u64 v[42:43], s[18:19], 0, v[66:67]
	s_waitcnt lgkmcnt(1)
	v_mfma_f32_16x16x32_bf16 v[38:41], v[46:49], v[62:65], v[38:41]
	v_add_f32_e64 v46, v110, v0
	v_add_f32_e64 v47, v111, v1
	v_lshl_add_u64 v[42:43], v[42:43], 0, v[92:93]
	v_pk_add_f32 v[46:47], v[112:113], v[46:47]
	v_mfma_f32_16x16x32_bf16 v[2:5], v[50:53], v[34:37], v[2:5]
	v_add_f32_e64 v46, v114, v46
	v_add_f32_e64 v47, v115, v47
	ds_read2_b64 v[50:53], v15 offset0:224 offset1:228
	ds_read2_b64 v[58:61], v15 offset0:232 offset1:236
	v_pk_add_f32 v[46:47], v[116:117], v[46:47]
	s_nop 0
	s_waitcnt lgkmcnt(0)
	s_barrier
	v_pk_add_f32 v[46:47], v[118:119], v[46:47]
	v_mfma_f32_16x16x32_bf16 v[10:13], v[50:53], v[62:65], v[10:13]
	v_add_f32_e64 v46, v122, v46
	v_add_f32_e64 v47, v123, v47
	s_add_u32 s18, s42, s47
	v_pk_add_f32 v[46:47], v[94:95], v[46:47]
	v_mfma_f32_16x16x32_bf16 v[10:13], v[58:61], v[34:37], v[10:13]
	v_add_f32_e64 v46, v96, v46
	v_add_f32_e64 v47, v97, v47
	s_addc_u32 s19, s43, 0
	v_pk_add_f32 v[46:47], v[98:99], v[46:47]
	s_add_i32 s46, s46, s6
	v_pk_add_f32 v[46:47], v[100:101], v[46:47]
	s_add_i32 s45, s45, s35
	v_pk_add_f32 v[46:47], v[102:103], v[46:47]
	s_add_i32 s44, s44, s30
	v_pk_add_f32 v[46:47], v[104:105], v[46:47]
	s_cmpk_gt_i32 s46, 0xff
	v_pk_add_f32 v[46:47], v[106:107], v[46:47]
	s_waitcnt vmcnt(0)
	v_mov_b32_e32 v44, v240
	v_mov_b32_e32 v45, v241
	v_lshlrev_b32_e32 v49, 16, v44
	v_pk_add_f32 v[46:47], v[108:109], v[46:47]
	v_and_b32_e32 v44, 0xffff0000, v44
	v_pk_add_f32 v[46:47], v[120:121], v[46:47]
	s_nop 0
	v_add_f32_e32 v0, v47, v157
	v_fmac_f32_e32 v0, v46, v124
	v_mul_f32_e32 v16, v0, v126
	v_add_f32_e32 v0, 0, v127
	v_add_f32_e32 v0, v158, v0
	v_pk_add_f32 v[46:47], v[128:129], v[0:1]
	s_nop 0
	v_pk_add_f32 v[46:47], v[130:131], v[46:47]
	s_nop 0
	v_pk_add_f32 v[46:47], v[132:133], v[46:47]
	s_nop 0
	v_pk_add_f32 v[46:47], v[134:135], v[46:47]
	s_nop 0
	v_pk_add_f32 v[46:47], v[136:137], v[46:47]
	s_nop 0
	v_pk_add_f32 v[46:47], v[154:155], v[46:47]
	s_nop 0
	v_pk_add_f32 v[46:47], v[138:139], v[46:47]
	s_nop 0
	v_pk_add_f32 v[46:47], v[140:141], v[46:47]
	s_nop 0
	v_pk_add_f32 v[46:47], v[142:143], v[46:47]
	s_nop 0
	v_pk_add_f32 v[46:47], v[144:145], v[46:47]
	s_nop 0
	v_pk_add_f32 v[46:47], v[146:147], v[46:47]
	s_nop 0
	v_pk_add_f32 v[46:47], v[148:149], v[46:47]
	s_nop 0
	v_pk_add_f32 v[46:47], v[150:151], v[46:47]
	s_nop 0
	v_pk_add_f32 v[46:47], v[152:153], v[46:47]
	s_nop 0
	v_pk_add_f32 v[16:17], v[16:17], v[46:47]
	s_nop 0
	v_add_f32_e32 v0, v17, v68
	v_fmac_f32_e32 v0, v16, v14
	v_mov_b32_e32 v46, v0
	s_nop 1
	v_permlane16_swap_b32_e32 v46, v0
	v_mfma_f32_16x16x32_bf16 v[14:17], v[54:57], v[34:37], v[38:41]
	v_and_b32_e32 v54, 0xffff0000, v45
	v_ashrrev_i32_e32 v91, 31, v90
	s_waitcnt lgkmcnt(0)
	v_add_f32_e32 v0, v0, v46
	v_mov_b32_e32 v38, v0
	s_nop 1
	v_permlane32_swap_b32_e32 v38, v0
	v_mul_f32_e32 v40, 0xbfb8aa3b, v49
	v_mul_f32_e32 v41, 0xbfb8aa3b, v44
	v_exp_f32_e32 v40, v40
	v_exp_f32_e32 v41, v41
	s_waitcnt lgkmcnt(0)
	v_add_f32_e32 v0, v0, v38
	v_div_scale_f32 v38, s[14:15], v0, v0, 1.0
	v_rcp_f32_e32 v46, v38
	v_pk_add_f32 v[40:41], v[40:41], 1.0 op_sel_hi:[1,0]
	v_fma_f32 v34, -v38, v46, 1.0
	v_fmac_f32_e32 v46, v34, v46
	v_div_scale_f32 v34, vcc, 1.0, v0, 1.0
	v_mul_f32_e32 v47, v34, v46
	v_fma_f32 v35, -v38, v47, v34
	v_fmac_f32_e32 v47, v35, v46
	v_fma_f32 v48, -v38, v47, v34
	v_mov_b32_e32 v36, v242
	v_mov_b32_e32 v37, v243
	v_mov_b32_e32 v38, v244
	v_mov_b32_e32 v39, v245
	v_mov_b32_e32 v34, v246
	v_mov_b32_e32 v35, v247
	v_div_fmas_f32 v46, v48, v46, v47
	v_div_scale_f32 v48, s[14:15], v41, v41, v44
	v_rcp_f32_e32 v50, v48
	v_div_fixup_f32 v0, v46, v0, 1.0
	v_pk_mul_f32 v[30:31], v[30:31], v[0:1] op_sel_hi:[1,0]
	v_pk_mul_f32 v[32:33], v[32:33], v[0:1] op_sel_hi:[1,0]
	v_fma_f32 v51, -v48, v50, 1.0
	v_fmac_f32_e32 v50, v51, v50
	v_div_scale_f32 v51, vcc, v44, v41, v44
	v_mul_f32_e32 v52, v51, v50
	v_fma_f32 v53, -v48, v52, v51
	v_fmac_f32_e32 v52, v53, v50
	v_fma_f32 v48, -v48, v52, v51
	v_div_fmas_f32 v48, v48, v50, v52
	v_div_fixup_f32 v41, v48, v41, v44
	v_lshlrev_b32_e32 v52, 16, v45
	v_mul_f32_e32 v44, 0xbfb8aa3b, v52
	v_mul_f32_e32 v45, 0xbfb8aa3b, v54
	v_exp_f32_e32 v44, v44
	v_exp_f32_e32 v45, v45
	v_rcp_f32_e32 v48, v40
	s_nop 0
	v_mul_f32_e32 v40, v49, v48
	v_pk_add_f32 v[44:45], v[44:45], 1.0 op_sel_hi:[1,0]
	v_pk_mul_f32 v[30:31], v[30:31], v[40:41]
	v_lshlrev_b64 v[46:47], 12, v[90:91]
	v_lshl_add_u64 v[46:47], s[18:19], 0, v[46:47]
	v_pk_mul_f32 v[26:27], v[26:27], v[0:1] op_sel_hi:[1,0]
	v_rcp_f32_e32 v40, v45
	s_nop 0
	v_mul_f32_e32 v41, v54, v40
	v_rcp_f32_e32 v40, v44
	s_nop 0
	v_mul_f32_e32 v40, v52, v40
	v_pk_mul_f32 v[32:33], v[32:33], v[40:41]
	v_cvt_pk_bf16_f32 v40, v30, v31
	v_cvt_pk_bf16_f32 v41, v32, v33
	v_lshl_add_u64 v[30:31], v[46:47], 0, v[92:93]
	global_store_dwordx2 v[30:31], v[40:41], off
	v_pk_mul_f32 v[28:29], v[28:29], v[0:1] op_sel_hi:[1,0]
	v_pk_mul_f32 v[22:23], v[22:23], v[0:1] op_sel_hi:[1,0]
	v_pk_mul_f32 v[24:25], v[24:25], v[0:1] op_sel_hi:[1,0]
	v_pk_mul_f32 v[20:21], v[20:21], v[0:1] op_sel_hi:[1,0]
	v_pk_mul_f32 v[6:7], v[6:7], v[0:1] op_sel_hi:[1,0]
	v_pk_mul_f32 v[8:9], v[8:9], v[0:1] op_sel_hi:[1,0]
	s_nop 0
	v_lshlrev_b32_e32 v48, 16, v36
	v_and_b32_e32 v36, 0xffff0000, v36
	v_mul_f32_e32 v44, 0xbfb8aa3b, v48
	v_mul_f32_e32 v45, 0xbfb8aa3b, v36
	v_exp_f32_e32 v44, v44
	v_exp_f32_e32 v45, v45
	v_and_b32_e32 v47, 0xffff0000, v37
	v_pk_mul_f32 v[2:3], v[2:3], v[0:1] op_sel_hi:[1,0]
	v_pk_mul_f32 v[4:5], v[4:5], v[0:1] op_sel_hi:[1,0]
	v_pk_add_f32 v[32:33], v[44:45], 1.0 op_sel_hi:[1,0]
	s_nop 0
	s_nop 0
	v_rcp_f32_e32 v40, v33
	s_nop 0
	v_mul_f32_e32 v33, v36, v40
	v_lshlrev_b32_e32 v45, 16, v37
	v_mul_f32_e32 v36, 0xbfb8aa3b, v45
	v_mul_f32_e32 v37, 0xbfb8aa3b, v47
	v_exp_f32_e32 v36, v36
	v_exp_f32_e32 v37, v37
	v_rcp_f32_e32 v40, v32
	s_nop 0
	v_mul_f32_e32 v32, v48, v40
	v_pk_add_f32 v[36:37], v[36:37], 1.0 op_sel_hi:[1,0]
	v_pk_mul_f32 v[26:27], v[26:27], v[32:33]
	v_cvt_pk_bf16_f32 v26, v26, v27
	v_rcp_f32_e32 v32, v37
	s_nop 0
	v_mul_f32_e32 v33, v47, v32
	s_nop 0
	v_lshlrev_b32_e32 v37, 16, v38
	v_and_b32_e32 v38, 0xffff0000, v38
	v_mul_f32_e32 v40, 0xbfb8aa3b, v37
	v_mul_f32_e32 v41, 0xbfb8aa3b, v38
	v_exp_f32_e32 v40, v40
	v_exp_f32_e32 v41, v41
	v_rcp_f32_e32 v32, v36
	s_nop 0
	v_mul_f32_e32 v32, v45, v32
	v_pk_mul_f32 v[28:29], v[28:29], v[32:33]
	v_pk_add_f32 v[32:33], v[40:41], 1.0 op_sel_hi:[1,0]
	s_nop 0
	v_cvt_pk_bf16_f32 v27, v28, v29
	global_store_dwordx2 v[30:31], v[26:27], off offset:32
	v_rcp_f32_e32 v26, v33
	s_nop 0
	v_mul_f32_e32 v27, v38, v26
	v_lshlrev_b32_e32 v38, 16, v39
	v_and_b32_e32 v39, 0xffff0000, v39
	v_mul_f32_e32 v28, 0xbfb8aa3b, v38
	v_mul_f32_e32 v29, 0xbfb8aa3b, v39
	v_exp_f32_e32 v28, v28
	v_exp_f32_e32 v29, v29
	v_rcp_f32_e32 v26, v32
	s_nop 0
	v_mul_f32_e32 v26, v37, v26
	v_pk_add_f32 v[28:29], v[28:29], 1.0 op_sel_hi:[1,0]
	v_pk_mul_f32 v[26:27], v[22:23], v[26:27]
	s_nop 0
	v_lshlrev_b32_e32 v37, 16, v34
	v_and_b32_e32 v34, 0xffff0000, v34
	v_cvt_pk_bf16_f32 v26, v26, v27
	v_rcp_f32_e32 v22, v29
	s_nop 0
	v_mul_f32_e32 v29, v39, v22
	v_mov_b32_e32 v22, v248
	v_mov_b32_e32 v23, v249
	v_mul_f32_e32 v32, 0xbfb8aa3b, v37
	v_mul_f32_e32 v33, 0xbfb8aa3b, v34
	v_exp_f32_e32 v32, v32
	v_exp_f32_e32 v33, v33
	v_rcp_f32_e32 v36, v28
	s_nop 0
	v_mul_f32_e32 v28, v38, v36
	v_pk_mul_f32 v[24:25], v[24:25], v[28:29]
	v_lshlrev_b32_e32 v36, 16, v35
	v_pk_add_f32 v[28:29], v[32:33], 1.0 op_sel_hi:[1,0]
	v_cvt_pk_bf16_f32 v27, v24, v25
	v_pk_mul_f32 v[24:25], v[18:19], v[0:1] op_sel_hi:[1,0]
	global_store_dwordx2 v[30:31], v[26:27], off offset:64
	v_rcp_f32_e32 v18, v29
	s_nop 0
	v_mul_f32_e32 v27, v34, v18
	v_and_b32_e32 v34, 0xffff0000, v35
	v_mul_f32_e32 v18, 0xbfb8aa3b, v36
	v_mul_f32_e32 v19, 0xbfb8aa3b, v34
	v_exp_f32_e32 v18, v18
	v_exp_f32_e32 v19, v19
	v_rcp_f32_e32 v26, v28
	s_nop 0
	v_mul_f32_e32 v26, v37, v26
	v_pk_add_f32 v[18:19], v[18:19], 1.0 op_sel_hi:[1,0]
	v_pk_mul_f32 v[24:25], v[24:25], v[26:27]
	s_nop 0
	v_lshlrev_b32_e32 v38, 16, v22
	v_rcp_f32_e32 v26, v19
	s_nop 0
	v_mul_f32_e32 v19, v34, v26
	v_and_b32_e32 v22, 0xffff0000, v22
	v_mov_b32_e32 v26, v250
	v_mov_b32_e32 v27, v251
	v_mov_b32_e32 v28, v252
	v_mov_b32_e32 v29, v253
	v_mov_b32_e32 v32, v254
	v_mov_b32_e32 v33, v255
	v_mul_f32_e32 v34, 0xbfb8aa3b, v38
	v_mul_f32_e32 v35, 0xbfb8aa3b, v22
	v_exp_f32_e32 v34, v34
	v_exp_f32_e32 v35, v35
	v_rcp_f32_e32 v37, v18
	s_nop 0
	v_mul_f32_e32 v18, v36, v37
	v_pk_mul_f32 v[18:19], v[20:21], v[18:19]
	v_cvt_pk_bf16_f32 v20, v24, v25
	v_pk_add_f32 v[24:25], v[34:35], 1.0 op_sel_hi:[1,0]
	v_cvt_pk_bf16_f32 v21, v18, v19
	global_store_dwordx2 v[30:31], v[20:21], off offset:96
	v_rcp_f32_e32 v18, v25
	s_nop 0
	v_mul_f32_e32 v19, v22, v18
	v_lshlrev_b32_e32 v25, 16, v23
	v_and_b32_e32 v23, 0xffff0000, v23
	v_mul_f32_e32 v20, 0xbfb8aa3b, v25
	v_mul_f32_e32 v21, 0xbfb8aa3b, v23
	v_exp_f32_e32 v20, v20
	v_exp_f32_e32 v21, v21
	v_rcp_f32_e32 v18, v24
	s_nop 0
	v_mul_f32_e32 v18, v38, v18
	v_pk_add_f32 v[20:21], v[20:21], 1.0 op_sel_hi:[1,0]
	v_pk_mul_f32 v[6:7], v[6:7], v[18:19]
	v_cvt_pk_bf16_f32 v6, v6, v7
	v_rcp_f32_e32 v18, v21
	s_nop 0
	v_mul_f32_e32 v19, v23, v18
	v_rcp_f32_e32 v18, v20
	s_nop 0
	v_mul_f32_e32 v18, v25, v18
	v_pk_mul_f32 v[8:9], v[8:9], v[18:19]
	s_nop 0
	v_lshlrev_b32_e32 v21, 16, v26
	v_and_b32_e32 v24, 0xffff0000, v26
	v_mul_f32_e32 v22, 0xbfb8aa3b, v21
	v_mul_f32_e32 v23, 0xbfb8aa3b, v24
	v_exp_f32_e32 v22, v22
	v_exp_f32_e32 v23, v23
	v_cvt_pk_bf16_f32 v7, v8, v9
	global_store_dwordx2 v[30:31], v[6:7], off offset:128
	v_pk_add_f32 v[18:19], v[22:23], 1.0 op_sel_hi:[1,0]
	s_nop 0
	s_nop 0
	v_rcp_f32_e32 v6, v19
	s_nop 0
	v_mul_f32_e32 v7, v24, v6
	v_lshlrev_b32_e32 v22, 16, v27
	v_and_b32_e32 v24, 0xffff0000, v27
	v_mul_f32_e32 v8, 0xbfb8aa3b, v22
	v_mul_f32_e32 v9, 0xbfb8aa3b, v24
	v_exp_f32_e32 v8, v8
	v_exp_f32_e32 v9, v9
	v_rcp_f32_e32 v6, v18
	s_nop 0
	v_mul_f32_e32 v6, v21, v6
	v_pk_add_f32 v[8:9], v[8:9], 1.0 op_sel_hi:[1,0]
	v_pk_mul_f32 v[2:3], v[2:3], v[6:7]
	v_cvt_pk_bf16_f32 v2, v2, v3
	v_rcp_f32_e32 v6, v9
	s_nop 0
	v_mul_f32_e32 v7, v24, v6
	s_nop 0
	v_lshlrev_b32_e32 v20, 16, v28
	v_and_b32_e32 v9, 0xffff0000, v28
	v_mul_f32_e32 v18, 0xbfb8aa3b, v20
	v_mul_f32_e32 v19, 0xbfb8aa3b, v9
	v_exp_f32_e32 v18, v18
	v_exp_f32_e32 v19, v19
	v_rcp_f32_e32 v6, v8
	s_nop 0
	v_mul_f32_e32 v6, v22, v6
	v_pk_mul_f32 v[4:5], v[4:5], v[6:7]
	v_pk_add_f32 v[6:7], v[18:19], 1.0 op_sel_hi:[1,0]
	s_nop 0
	v_cvt_pk_bf16_f32 v3, v4, v5
	global_store_dwordx2 v[30:31], v[2:3], off offset:160
	v_pk_mul_f32 v[2:3], v[14:15], v[0:1] op_sel_hi:[1,0]
	v_rcp_f32_e32 v4, v7
	s_nop 0
	v_mul_f32_e32 v5, v9, v4
	v_lshlrev_b32_e32 v18, 16, v29
	v_and_b32_e32 v19, 0xffff0000, v29
	v_mul_f32_e32 v8, 0xbfb8aa3b, v18
	v_mul_f32_e32 v9, 0xbfb8aa3b, v19
	v_exp_f32_e32 v8, v8
	v_exp_f32_e32 v9, v9
	v_rcp_f32_e32 v4, v6
	s_nop 0
	v_mul_f32_e32 v4, v20, v4
	v_pk_add_f32 v[8:9], v[8:9], 1.0 op_sel_hi:[1,0]
	v_pk_mul_f32 v[2:3], v[2:3], v[4:5]
	v_pk_mul_f32 v[4:5], v[16:17], v[0:1] op_sel_hi:[1,0]
	v_cvt_pk_bf16_f32 v2, v2, v3
	v_rcp_f32_e32 v6, v9
	s_nop 0
	v_mul_f32_e32 v7, v19, v6
	s_nop 0
	v_lshlrev_b32_e32 v16, 16, v32
	v_and_b32_e32 v9, 0xffff0000, v32
	v_mul_f32_e32 v14, 0xbfb8aa3b, v16
	v_mul_f32_e32 v15, 0xbfb8aa3b, v9
	v_exp_f32_e32 v14, v14
	v_exp_f32_e32 v15, v15
	v_rcp_f32_e32 v6, v8
	s_nop 0
	v_mul_f32_e32 v6, v18, v6
	v_pk_mul_f32 v[4:5], v[4:5], v[6:7]
	v_pk_add_f32 v[6:7], v[14:15], 1.0 op_sel_hi:[1,0]
	s_nop 0
	v_cvt_pk_bf16_f32 v3, v4, v5
	global_store_dwordx2 v[30:31], v[2:3], off offset:192
	v_pk_mul_f32 v[2:3], v[10:11], v[0:1] op_sel_hi:[1,0]
	v_rcp_f32_e32 v4, v7
	s_nop 0
	v_mul_f32_e32 v5, v9, v4
	v_lshlrev_b32_e32 v14, 16, v33
	v_and_b32_e32 v15, 0xffff0000, v33
	v_mul_f32_e32 v8, 0xbfb8aa3b, v14
	v_mul_f32_e32 v9, 0xbfb8aa3b, v15
	v_exp_f32_e32 v8, v8
	v_exp_f32_e32 v9, v9
	v_rcp_f32_e32 v4, v6
	s_nop 0
	v_mul_f32_e32 v4, v16, v4
	v_pk_add_f32 v[8:9], v[8:9], 1.0 op_sel_hi:[1,0]
	v_pk_mul_f32 v[2:3], v[2:3], v[4:5]
	v_pk_mul_f32 v[4:5], v[12:13], v[0:1] op_sel_hi:[1,0]
	v_cvt_pk_bf16_f32 v2, v2, v3
	v_rcp_f32_e32 v0, v9
	s_nop 0
	v_mul_f32_e32 v7, v15, v0
	v_rcp_f32_e32 v0, v8
	s_nop 0
	v_mul_f32_e32 v6, v14, v0
	v_pk_mul_f32 v[4:5], v[4:5], v[6:7]
	s_nop 0
	v_cvt_pk_bf16_f32 v3, v4, v5
	global_store_dwordx2 v[30:31], v[2:3], off offset:224
	s_cbranch_scc1 .LBB0_409
.LBB0_403:
	s_and_b32 s18, s44, 0x180
	s_and_b32 s24, s45, 0xffffff80
	s_lshl_b32 s47, s18, 1
	s_add_u32 s14, s2, s47
	s_addc_u32 s15, s36, 0
	s_add_u32 s22, s1, s47
	s_addc_u32 s23, s37, 0
	s_or_b32 s18, s18, s0
	s_ashr_i32 s19, s18, 31
	s_lshl_b64 s[18:19], s[18:19], 9
	v_mov_b32_e32 v0, v204
	s_add_u32 s18, s38, s18
	s_addc_u32 s19, s39, s19
	v_lshlrev_b32_e32 v4, 4, v0
	v_ashrrev_i32_e32 v12, 4, v0
	v_ashrrev_i32_e32 v14, 3, v0
	v_and_b32_e32 v10, 0xf0, v4
	v_mov_b32_e32 v11, v1
	v_and_b32_e32 v18, 0x70, v4
	v_mov_b32_e32 v19, v1
	v_ashrrev_i32_e32 v13, 31, v12
	v_ashrrev_i32_e32 v15, 31, v14
	v_add_u32_e32 v8, 0x200, v0
	v_lshl_add_u64 v[2:3], s[22:23], 0, v[10:11]
	v_lshl_add_u64 v[4:5], s[18:19], 0, v[18:19]
	v_lshlrev_b64 v[6:7], 12, v[12:13]
	v_lshlrev_b64 v[20:21], 9, v[14:15]
	v_ashrrev_i32_e32 v16, 4, v8
	v_lshl_add_u64 v[54:55], v[2:3], 0, v[6:7]
	v_lshl_add_u64 v[6:7], v[4:5], 0, v[20:21]
	v_ashrrev_i32_e32 v17, 31, v16
	v_ashrrev_i32_e32 v22, 3, v8
	global_load_dwordx4 v[34:37], v[54:55], off
	global_load_dwordx4 v[38:41], v[6:7], off
	v_lshlrev_b64 v[6:7], 12, v[16:17]
	v_ashrrev_i32_e32 v23, 31, v22
	v_lshl_add_u64 v[56:57], v[2:3], 0, v[6:7]
	v_lshlrev_b64 v[24:25], 9, v[22:23]
	v_readfirstlane_b32 s22, v0
	v_lshl_add_u64 v[2:3], v[4:5], 0, v[24:25]
	global_load_dwordx4 v[42:45], v[56:57], off
	global_load_dwordx4 v[46:49], v[2:3], off
	v_and_b32_e32 v66, 15, v0
	s_ashr_i32 s22, s22, 2
	v_bfe_u32 v67, v0, 4, 2
	s_and_b32 s22, s22, -16
	v_or_b32_e32 v0, s24, v66
	v_add_u32_e32 v90, s22, v0
	v_mov_b64_e32 v[2:3], s[14:15]
	v_mad_i64_i32 v[2:3], s[14:15], v90, s59, v[2:3]
	v_lshlrev_b32_e32 v0, 4, v67
	v_lshl_add_u64 v[26:27], v[2:3], 0, v[0:1]
	global_load_dwordx4 v[6:9], v[26:27], off nt
	global_load_dwordx4 v[2:5], v[26:27], off offset:64 nt
	s_movk_i32 s7, 0x110
	v_mul_lo_u32 v15, v12, s7
	v_add_u32_e32 v23, 0, v10
	global_load_dwordx4 v[10:13], v[26:27], off offset:128 nt
	s_movk_i32 s6, 0x90
	v_mul_lo_u32 v14, v14, s6
	v_mad_u32_u24 v17, v66, s7, 0
	v_add_u32_e32 v28, 0, v18
	v_mul_lo_u32 v16, v16, s7
	v_add_u32_e32 v143, v17, v0
	v_add_u32_e32 v145, v23, v15
	v_add_u32_e32 v147, v28, v14
	v_add_u32_e32 v149, v23, v16
	global_load_dwordx4 v[14:17], v[26:27], off offset:192 nt
	v_mul_lo_u32 v22, v22, s6
	s_mov_b32 s6, 0x40000
	v_add_u32_e32 v151, v28, v22
	v_add_co_u32_e32 v22, vcc, s6, v54
	v_lshl_add_u64 v[20:21], s[18:19], 0, v[20:21]
	s_nop 0
	v_addc_co_u32_e32 v23, vcc, 0, v55, vcc
	v_add_co_u32_e32 v26, vcc, s6, v56
	v_lshl_add_u64 v[24:25], s[18:19], 0, v[24:25]
	s_nop 0
	v_addc_co_u32_e32 v27, vcc, 0, v57, vcc
	v_lshl_add_u64 v[70:71], v[20:21], 0, v[18:19]
	v_lshl_add_u64 v[72:73], v[24:25], 0, v[18:19]
	global_load_dwordx4 v[18:21], v[22:23], off
	s_nop 0
	global_load_dwordx4 v[22:25], v[70:71], off offset:128
	s_nop 0
	global_load_dwordx4 v[26:29], v[26:27], off
	s_nop 0
	global_load_dwordx4 v[30:33], v[72:73], off offset:128
	v_xor_b32_e32 v0, 16, v209
	v_lshlrev_b32_e32 v92, 3, v67
	s_mov_b32 s14, 0xf149f2ca
	s_mov_b32 s6, 0x80000
	s_waitcnt vmcnt(11)
	ds_write_b128 v145, v[34:37]
	s_waitcnt vmcnt(10)
	ds_write_b128 v147, v[38:41] offset:34816
	s_waitcnt vmcnt(9)
	ds_write_b128 v149, v[42:45]
	s_waitcnt vmcnt(8)
	ds_write_b128 v151, v[46:49] offset:34816
	s_waitcnt lgkmcnt(0)
	s_barrier
	v_mad_u32_u24 v239, v90, s59, v92
	v_add_u32_e32 v239, s47, v239
	global_load_dwordx2 v[240:241], v239, s[40:41] nt
	global_load_dwordx2 v[242:243], v239, s[40:41] offset:32 nt
	global_load_dwordx2 v[244:245], v239, s[40:41] offset:64 nt
	global_load_dwordx2 v[246:247], v239, s[40:41] offset:96 nt
	global_load_dwordx2 v[248:249], v239, s[40:41] offset:128 nt
	global_load_dwordx2 v[250:251], v239, s[40:41] offset:160 nt
	global_load_dwordx2 v[252:253], v239, s[40:41] offset:192 nt
	global_load_dwordx2 v[254:255], v239, s[40:41] offset:224 nt
	ds_read_b128 v[34:37], v143
	ds_read_b128 v[38:41], v143 offset:64
	ds_read_b128 v[42:45], v143 offset:4352
	ds_read_b128 v[46:49], v143 offset:4416
	s_waitcnt vmcnt(15) lgkmcnt(3)
	v_mfma_f32_16x16x32_bf16 v[34:37], v[34:37], v[6:9], 0
	ds_read_b128 v[50:53], v143 offset:8704
	ds_read_b128 v[58:61], v143 offset:8768
	s_waitcnt lgkmcnt(3)
	v_mfma_f32_16x16x32_bf16 v[42:45], v[42:45], v[6:9], 0
	s_waitcnt vmcnt(14)
	v_mfma_f32_16x16x32_bf16 v[34:37], v[38:41], v[2:5], v[34:37]
	s_waitcnt lgkmcnt(2)
	v_mfma_f32_16x16x32_bf16 v[38:41], v[46:49], v[2:5], v[42:45]
	s_nop 3
	ds_read_b128 v[42:45], v143 offset:128
	ds_read_b128 v[46:49], v143 offset:192
	s_waitcnt vmcnt(13) lgkmcnt(1)
	v_mfma_f32_16x16x32_bf16 v[34:37], v[42:45], v[10:13], v[34:37]
	ds_read_b128 v[42:45], v143 offset:4480
	ds_read_b128 v[62:65], v143 offset:4544
	v_mfma_f32_16x16x32_bf16 v[50:53], v[50:53], v[6:9], 0
	s_waitcnt lgkmcnt(1)
	v_mfma_f32_16x16x32_bf16 v[38:41], v[42:45], v[10:13], v[38:41]
	ds_read_b128 v[42:45], v143 offset:8832
	s_waitcnt vmcnt(12)
	v_mfma_f32_16x16x32_bf16 v[34:37], v[46:49], v[14:17], v[34:37]
	ds_read_b128 v[46:49], v143 offset:8896
	v_mfma_f32_16x16x32_bf16 v[50:53], v[58:61], v[2:5], v[50:53]
	v_and_b32_e32 v58, 64, v209
	s_waitcnt lgkmcnt(2)
	v_mfma_f32_16x16x32_bf16 v[38:41], v[62:65], v[14:17], v[38:41]
	v_add_u32_e32 v62, 64, v58
	ds_read_b128 v[58:61], v143 offset:13056
	v_cmp_lt_i32_e32 vcc, v0, v62
	s_waitcnt lgkmcnt(2)
	v_mfma_f32_16x16x32_bf16 v[42:45], v[42:45], v[10:13], v[50:53]
	v_cndmask_b32_e32 v0, v209, v0, vcc
	v_lshlrev_b32_e32 v91, 2, v0
	s_nop 0
	ds_read_b128 v[50:53], v143 offset:13120
	s_waitcnt lgkmcnt(2)
	v_mfma_f32_16x16x32_bf16 v[42:45], v[46:49], v[14:17], v[42:45]
	ds_read_b128 v[46:49], v143 offset:13184
	v_xor_b32_e32 v0, 32, v209
	v_cmp_lt_i32_e32 vcc, v0, v62
	s_waitcnt lgkmcnt(2)
	v_mfma_f32_16x16x32_bf16 v[58:61], v[58:61], v[6:9], 0
	ds_read_b128 v[62:65], v143 offset:13248
	v_cndmask_b32_e32 v0, v209, v0, vcc
	v_lshlrev_b32_e32 v125, 2, v0
	s_waitcnt lgkmcnt(2)
	v_mfma_f32_16x16x32_bf16 v[50:53], v[50:53], v[2:5], v[58:61]
	v_mul_u32_u24_e32 v0, 0x90, v66
	v_add3_u32 v93, 0, v92, v0
	s_waitcnt lgkmcnt(1)
	v_mfma_f32_16x16x32_bf16 v[46:49], v[46:49], v[10:13], v[50:53]
	v_mul_f32_e64 v58, v40, s34
	v_mul_f32_e64 v59, v41, s34
	v_pk_mul_f32 v[60:61], v[38:39], s[34:35] op_sel_hi:[1,0]
	v_max_f32_e32 v39, v58, v59
	s_waitcnt lgkmcnt(0)
	v_mfma_f32_16x16x32_bf16 v[46:49], v[62:65], v[14:17], v[46:49]
	v_mul_f32_e64 v62, v36, s34
	v_mul_f32_e64 v63, v37, s34
	v_pk_mul_f32 v[64:65], v[34:35], s[34:35] op_sel_hi:[1,0]
	v_pk_mul_f32 v[34:35], v[44:45], s[34:35] op_sel_hi:[1,0]
	v_max_f32_e32 v0, v64, v65
	v_max_f32_e32 v38, v62, v63
	s_nop 1
	v_pk_mul_f32 v[66:67], v[48:49], s[34:35] op_sel_hi:[1,0]
	v_max3_f32 v39, v60, v61, v39
	v_pk_mul_f32 v[36:37], v[42:43], s[34:35] op_sel_hi:[1,0]
	v_pk_mul_f32 v[68:69], v[46:47], s[34:35] op_sel_hi:[1,0]
	v_max3_f32 v0, v0, v38, v39
	v_max_f32_e32 v38, v34, v35
	v_max_f32_e32 v39, v66, v67
	v_max3_f32 v38, v36, v37, v38
	v_max3_f32 v39, v68, v69, v39
	v_max3_f32 v0, v0, v38, v39
	v_mov_b32_e32 v40, v0
	s_nop 1
	v_permlane16_swap_b32_e32 v40, v0
	v_add_co_u32_e32 v50, vcc, s6, v54
	s_waitcnt lgkmcnt(0)
	v_max_f32_e32 v40, v40, v40
	v_max_f32_e32 v0, v0, v40
	v_mov_b32_e32 v74, v0
	s_nop 1
	v_permlane32_swap_b32_e32 v74, v0
	v_addc_co_u32_e32 v51, vcc, 0, v55, vcc
	v_add_co_u32_e32 v38, vcc, s6, v56
	s_waitcnt lgkmcnt(0)
	v_max3_f32 v95, v0, v74, s14
	v_sub_f32_e32 v0, v36, v95
	v_exp_f32_e32 v94, v0
	v_sub_f32_e32 v0, v37, v95
	v_exp_f32_e32 v96, v0
	v_sub_f32_e32 v0, v34, v95
	v_exp_f32_e32 v98, v0
	v_sub_f32_e32 v0, v35, v95
	v_exp_f32_e32 v100, v0
	v_sub_f32_e32 v0, v68, v95
	v_exp_f32_e32 v102, v0
	v_sub_f32_e32 v0, v69, v95
	v_exp_f32_e32 v104, v0
	v_sub_f32_e32 v0, v66, v95
	v_exp_f32_e32 v106, v0
	v_sub_f32_e32 v0, v67, v95
	v_exp_f32_e32 v108, v0
	v_addc_co_u32_e32 v39, vcc, 0, v57, vcc
	v_cvt_pk_bf16_f32 v34, v94, v96
	v_cvt_pk_bf16_f32 v35, v98, v100
	v_cvt_pk_bf16_f32 v36, v102, v104
	v_cvt_pk_bf16_f32 v37, v106, v108
	v_mov_b32_e32 v0, v1
	global_load_dwordx4 v[42:45], v[50:51], off
	s_nop 0
	global_load_dwordx4 v[38:41], v[38:39], off
	s_nop 0
	global_load_dwordx4 v[50:53], v[70:71], off offset:256
	global_load_dwordx4 v[46:49], v[72:73], off offset:256
	s_mov_b32 s6, 0xc0000
	v_add_u32_e32 v0, v93, v0
	v_add_u32_e32 v66, 0x8800, v0
	v_add_u32_e32 v74, 0x9000, v0
	v_add_u32_e32 v97, 0x9800, v0
	ds_read2_b64 v[82:85], v66 offset1:4
	ds_read2_b64 v[86:89], v66 offset0:8 offset1:12
	ds_read2_b64 v[66:69], v74 offset0:32 offset1:36
	ds_read2_b64 v[74:77], v74 offset0:40 offset1:44
	ds_read2_b64 v[78:81], v97 offset0:64 offset1:68
	ds_read2_b64 v[126:129], v97 offset0:72 offset1:76
	v_add_u32_e32 v97, 0xa000, v0
	ds_read2_b64 v[130:133], v97 offset0:96 offset1:100
	ds_read2_b64 v[134:137], v97 offset0:104 offset1:108
	v_add_u32_e32 v97, 0xa800, v0
	ds_read2_b64 v[138:141], v97 offset0:128 offset1:132
	ds_read2_b64 v[152:155], v97 offset0:136 offset1:140
	v_add_u32_e32 v97, 0xb000, v0
	ds_read2_b64 v[158:161], v97 offset0:160 offset1:164
	ds_read2_b64 v[162:165], v97 offset0:168 offset1:172
	v_add_u32_e32 v97, 0xb800, v0
	v_add_u32_e32 v0, 0xc000, v0
	ds_read2_b64 v[166:169], v97 offset0:192 offset1:196
	ds_read2_b64 v[170:173], v97 offset0:200 offset1:204
	ds_read2_b64 v[174:177], v0 offset0:224 offset1:228
	ds_read2_b64 v[178:181], v0 offset0:232 offset1:236
	s_waitcnt vmcnt(15)
	ds_write_b128 v145, v[18:21] offset:17408
	s_waitcnt vmcnt(14)
	ds_write_b128 v147, v[22:25] offset:53248
	s_waitcnt vmcnt(13)
	ds_write_b128 v149, v[26:29] offset:17408
	s_waitcnt vmcnt(12)
	ds_write_b128 v151, v[30:33] offset:53248
	s_waitcnt lgkmcnt(0)
	s_barrier
	ds_read_b128 v[18:21], v143 offset:17408
	ds_read_b128 v[22:25], v143 offset:17472
	ds_read_b128 v[26:29], v143 offset:17536
	s_waitcnt lgkmcnt(2)
	v_mfma_f32_16x16x32_bf16 v[18:21], v[18:21], v[6:9], 0
	ds_read_b128 v[30:33], v143 offset:21824
	v_sub_f32_e32 v97, 0xf149f2ca, v95
	v_sub_f32_e32 v0, v64, v95
	s_waitcnt lgkmcnt(2)
	v_mfma_f32_16x16x32_bf16 v[18:21], v[22:25], v[2:5], v[18:21]
	ds_read_b128 v[22:25], v143 offset:17600
	v_exp_f32_e32 v0, v0
	s_waitcnt lgkmcnt(2)
	v_mfma_f32_16x16x32_bf16 v[18:21], v[26:29], v[10:13], v[18:21]
	ds_read_b128 v[26:29], v143 offset:21760
	s_waitcnt lgkmcnt(1)
	v_mfma_f32_16x16x32_bf16 v[182:185], v[22:25], v[14:17], v[18:21]
	s_nop 4
	ds_read_b128 v[18:21], v143 offset:21888
	s_waitcnt lgkmcnt(1)
	v_mfma_f32_16x16x32_bf16 v[22:25], v[26:29], v[6:9], 0
	v_sub_f32_e32 v26, v65, v95
	v_exp_f32_e32 v156, v26
	ds_read_b128 v[26:29], v143 offset:21952
	v_mfma_f32_16x16x32_bf16 v[22:25], v[30:33], v[2:5], v[22:25]
	v_sub_f32_e32 v30, v62, v95
	v_exp_f32_e32 v110, v30
	ds_read_b128 v[30:33], v143 offset:26112
	s_waitcnt lgkmcnt(2)
	v_mfma_f32_16x16x32_bf16 v[18:21], v[18:21], v[10:13], v[22:25]
	v_cvt_pk_bf16_f32 v216, v0, v156
	s_nop 1
	v_sub_f32_e32 v22, v63, v95
	v_exp_f32_e32 v112, v22
	ds_read_b128 v[22:25], v143 offset:26176
	s_waitcnt lgkmcnt(2)
	v_mfma_f32_16x16x32_bf16 v[190:193], v[26:29], v[14:17], v[18:21]
	v_cvt_pk_bf16_f32 v217, v110, v112
	s_nop 1
	v_sub_f32_e32 v18, v60, v95
	v_exp_f32_e32 v114, v18
	ds_read_b128 v[18:21], v143 offset:26240
	s_waitcnt lgkmcnt(2)
	v_mfma_f32_16x16x32_bf16 v[26:29], v[30:33], v[6:9], 0
	v_sub_f32_e32 v30, v61, v95
	v_exp_f32_e32 v116, v30
	ds_read_b128 v[30:33], v143 offset:26304
	s_waitcnt lgkmcnt(2)
	v_mfma_f32_16x16x32_bf16 v[22:25], v[22:25], v[2:5], v[26:29]
	v_cvt_pk_bf16_f32 v218, v114, v116
	s_nop 1
	v_sub_f32_e32 v26, v58, v95
	v_exp_f32_e32 v118, v26
	ds_read_b128 v[26:29], v143 offset:30464
	s_waitcnt lgkmcnt(2)
	v_mfma_f32_16x16x32_bf16 v[18:21], v[18:21], v[10:13], v[22:25]
	v_sub_f32_e32 v58, v59, v95
	v_exp_f32_e32 v59, v97
	v_exp_f32_e32 v122, v58
	ds_read_b128 v[22:25], v143 offset:30528
	s_waitcnt lgkmcnt(2)
	v_mfma_f32_16x16x32_bf16 v[194:197], v[30:33], v[14:17], v[18:21]
	ds_read_b128 v[30:33], v143 offset:30656
	v_cmp_neq_f32_e32 vcc, 1.0, v59
	s_cmp_lg_u64 vcc, 0
	ds_read_b128 v[18:21], v143 offset:30592
	s_waitcnt lgkmcnt(3)
	v_mfma_f32_16x16x32_bf16 v[26:29], v[26:29], v[6:9], 0
	v_mul_f32_e32 v120, 0, v59
	s_cselect_b64 vcc, -1, 0
	v_cndmask_b32_e32 v198, 0, v120, vcc
	s_waitcnt lgkmcnt(2)
	v_mfma_f32_16x16x32_bf16 v[22:25], v[22:25], v[2:5], v[26:29]
	v_mov_b32_e32 v199, v198
	v_mov_b32_e32 v200, v198
	v_mov_b32_e32 v201, v198
	s_waitcnt lgkmcnt(0)
	v_mfma_f32_16x16x32_bf16 v[18:21], v[18:21], v[10:13], v[22:25]
	v_cvt_pk_bf16_f32 v219, v118, v122
	v_mfma_f32_16x16x32_bf16 v[220:223], v[30:33], v[14:17], v[18:21]
	s_nop 0
	v_mfma_f32_16x16x32_bf16 v[18:21], v[66:69], v[216:219], v[198:201]
	v_mfma_f32_16x16x32_bf16 v[58:61], v[74:77], v[34:37], v[18:21]
	v_mfma_f32_16x16x32_bf16 v[18:21], v[78:81], v[216:219], v[198:201]
	v_mfma_f32_16x16x32_bf16 v[62:65], v[126:129], v[34:37], v[18:21]
	v_mul_f32_e64 v126, v192, s34
	v_mul_f32_e64 v127, v193, s34
	s_nop 0
	v_pk_mul_f32 v[128:129], v[222:223], s[34:35] op_sel_hi:[1,0]
	s_nop 2
	v_add_co_u32_e32 v18, vcc, s6, v54
	v_mfma_f32_16x16x32_bf16 v[26:29], v[130:133], v[216:219], v[198:201]
	s_nop 0
	v_addc_co_u32_e32 v19, vcc, 0, v55, vcc
	v_add_co_u32_e32 v20, vcc, s6, v56
	v_mfma_f32_16x16x32_bf16 v[66:69], v[134:137], v[34:37], v[26:29]
	s_nop 0
	v_addc_co_u32_e32 v21, vcc, 0, v57, vcc
	global_load_dwordx4 v[22:25], v[18:19], off
	s_nop 0
	global_load_dwordx4 v[18:21], v[20:21], off
	s_nop 0
	global_load_dwordx4 v[30:33], v[70:71], off offset:384
	global_load_dwordx4 v[26:29], v[72:73], off offset:384
	v_mfma_f32_16x16x32_bf16 v[54:57], v[138:141], v[216:219], v[198:201]
	v_mul_f32_e64 v136, v190, s34
	v_mul_f32_e64 v137, v191, s34
	v_pk_mul_f32 v[138:139], v[184:185], s[34:35] op_sel_hi:[1,0]
	v_pk_mul_f32 v[140:141], v[182:183], s[34:35] op_sel_hi:[1,0]
	v_mfma_f32_16x16x32_bf16 v[70:73], v[152:155], v[34:37], v[54:57]
	v_mul_f32_e64 v130, v196, s34
	v_mul_f32_e64 v131, v197, s34
	v_max_f32_e32 v78, v140, v141
	v_max_f32_e32 v79, v138, v139
	v_mfma_f32_16x16x32_bf16 v[54:57], v[158:161], v[216:219], v[198:201]
	v_mul_f32_e64 v134, v194, s34
	v_mul_f32_e64 v135, v195, s34
	v_pk_mul_f32 v[132:133], v[220:221], s[34:35] op_sel_hi:[1,0]
	v_mfma_f32_16x16x32_bf16 v[74:77], v[162:165], v[34:37], v[54:57]
	v_mfma_f32_16x16x32_bf16 v[82:85], v[82:85], v[216:219], v[198:201]
	s_nop 2
	v_max_f32_e32 v54, v126, v127
	v_max3_f32 v80, v136, v137, v54
	v_max3_f32 v97, v78, v79, v80
	v_mfma_f32_16x16x32_bf16 v[54:57], v[166:169], v[216:219], v[198:201]
	v_max_f32_e32 v78, v130, v131
	v_max3_f32 v99, v134, v135, v78
	v_mfma_f32_16x16x32_bf16 v[78:81], v[170:173], v[34:37], v[54:57]
	s_nop 4
	v_max_f32_e32 v54, v128, v129
	v_max3_f32 v54, v132, v133, v54
	v_max3_f32 v97, v97, v99, v54
	v_mov_b32_e32 v99, v97
	s_nop 1
	v_permlane16_swap_b32_e32 v99, v97
	v_mfma_f32_16x16x32_bf16 v[54:57], v[174:177], v[216:219], v[198:201]
	s_waitcnt lgkmcnt(0)
	v_max_f32_e32 v99, v99, v99
	v_max_f32_e32 v97, v97, v99
	v_mov_b32_e32 v99, v97
	s_nop 1
	v_permlane32_swap_b32_e32 v99, v97
	v_mfma_f32_16x16x32_bf16 v[54:57], v[178:181], v[34:37], v[54:57]
	s_waitcnt lgkmcnt(0)
	v_max3_f32 v142, v95, v97, v99
	v_sub_f32_e32 v95, v95, v142
	v_exp_f32_e32 v124, v95
	v_mfma_f32_16x16x32_bf16 v[34:37], v[86:89], v[34:37], v[82:85]
	v_cmp_neq_f32_e32 vcc, 1.0, v124
	s_cbranch_vccz .LBB0_405
	s_nop 5
	v_pk_mul_f32 v[36:37], v[36:37], v[124:125] op_sel_hi:[1,0]
	v_pk_mul_f32 v[34:35], v[34:35], v[124:125] op_sel_hi:[1,0]
	v_pk_mul_f32 v[60:61], v[60:61], v[124:125] op_sel_hi:[1,0]
	v_pk_mul_f32 v[58:59], v[58:59], v[124:125] op_sel_hi:[1,0]
	v_pk_mul_f32 v[64:65], v[64:65], v[124:125] op_sel_hi:[1,0]
	v_pk_mul_f32 v[62:63], v[62:63], v[124:125] op_sel_hi:[1,0]
	v_pk_mul_f32 v[68:69], v[68:69], v[124:125] op_sel_hi:[1,0]
	v_pk_mul_f32 v[66:67], v[66:67], v[124:125] op_sel_hi:[1,0]
	v_pk_mul_f32 v[72:73], v[72:73], v[124:125] op_sel_hi:[1,0]
	v_pk_mul_f32 v[70:71], v[70:71], v[124:125] op_sel_hi:[1,0]
	v_pk_mul_f32 v[76:77], v[76:77], v[124:125] op_sel_hi:[1,0]
	v_pk_mul_f32 v[74:75], v[74:75], v[124:125] op_sel_hi:[1,0]
	v_pk_mul_f32 v[80:81], v[80:81], v[124:125] op_sel_hi:[1,0]
	v_pk_mul_f32 v[78:79], v[78:79], v[124:125] op_sel_hi:[1,0]
	v_pk_mul_f32 v[56:57], v[56:57], v[124:125] op_sel_hi:[1,0]
	v_pk_mul_f32 v[54:55], v[54:55], v[124:125] op_sel_hi:[1,0]
